# P2 tail weight conversion split statically between the workgroups with 8 and with 9 GEMM units
# speedup vs baseline: 1.0160x; 1.0095x over previous
.LBB0_483:
	s_cmpk_lg_u32 s95, 0x100
	s_cbranch_scc1 .Lconv_orig
	s_and_b32 s1, s81, 0x7f
	s_lshl_b32 s2, s1, 3
	s_ashr_i32 s1, s20, 6
	s_add_i32 s2, s1, s2
	s_movk_i32 s0, 0x80
	s_movk_i32 s99, 0x3c00
	s_cmpk_lt_u32 s81, 0x80
	s_cbranch_scc0 .Lconv_go
	s_addk_i32 s2, 0x3c00
	s_movk_i32 s99, 0x4c00
.Lconv_go:
	s_waitcnt vmcnt(0) lgkmcnt(0)
	s_barrier
	s_branch .Lconv_body
.Lconv_orig:
	s_movk_i32 s99, 0x4c00
	s_sub_i32 s1, 0x880, s70
	s_sub_i32 s0, s95, s1
	s_cmp_lt_i32 s0, 1
	s_cselect_b64 s[4:5], -1, 0
	s_cmp_lt_i32 s81, s1
	s_cselect_b64 s[6:7], -1, 0
	s_or_b64 s[4:5], s[6:7], s[4:5]
	s_and_b64 vcc, exec, s[4:5]
	s_cbranch_vccnz .LBB0_499
	s_sub_i32 s1, s81, s1
	s_lshl_b32 s2, s1, 3
	s_ashr_i32 s1, s20, 6
	s_add_i32 s2, s1, s2
	s_cmpk_gt_i32 s2, 0x4bff
	s_waitcnt vmcnt(0) lgkmcnt(0)
	s_barrier
	s_cbranch_scc1 .LBB0_499
.Lconv_body:
	s_lshl_b32 s1, s1, 14
	v_bfe_u32 v3, v1, 5, 1
	v_and_b32_e32 v2, 31, v1
	s_add_i32 s1, s1, 0
	v_lshlrev_b32_e32 v4, 2, v2
	v_mul_u32_u24_e32 v6, 0x84, v3
	v_add3_u32 v20, s1, v4, v6
	v_lshlrev_b32_e32 v4, 4, v1
	v_mov_b32_e32 v5, 0
	v_and_b32_e32 v4, 48, v4
	v_bfe_u32 v21, v1, 2, 4
	v_mul_u32_u24_e32 v8, 0x84, v4
	v_lshl_add_u64 v[14:15], s[18:19], 0, v[4:5]
	v_and_b32_e32 v4, 60, v1
	v_bfe_u32 v24, v1, 3, 3
	v_lshlrev_b32_e32 v1, 3, v1
	v_and_b32_e32 v1, 56, v1
	s_mov_b64 s[8:9], 0x4400000
	v_add3_u32 v22, s1, v8, v4
	v_lshlrev_b32_e32 v4, 1, v1
	v_lshl_add_u64 v[6:7], v[14:15], 0, s[8:9]
	v_lshl_add_u64 v[8:9], s[18:19], 0, v[4:5]
	s_mov_b64 s[8:9], 0x2400000
	v_mul_u32_u24_e32 v10, 0x84, v1
	v_lshl_add_u64 v[8:9], v[8:9], 0, s[8:9]
	v_lshlrev_b32_e32 v1, 2, v24
	s_mov_b64 s[8:9], 0x2fc00000
	v_add3_u32 v1, s1, v10, v1
	v_lshl_add_u64 v[10:11], v[14:15], 0, s[8:9]
	s_mov_b64 s[8:9], 0x1c00000
	v_lshl_add_u64 v[12:13], v[14:15], 0, s[8:9]
	s_mov_b64 s[8:9], 0x1800000
	s_lshl_b32 s6, s0, 3
	s_mov_b32 s5, 0
	v_or_b32_e32 v23, 16, v21
	v_or_b32_e32 v25, 8, v24
	v_or_b32_e32 v26, 16, v24
	v_or_b32_e32 v27, 24, v24
	v_lshl_add_u64 v[14:15], v[14:15], 0, s[8:9]
	s_lshl_b32 s7, s2, 5
	s_lshl_b32 s8, s0, 8
	s_lshl_b32 s9, s2, 6
	s_lshl_b32 s10, s0, 9
	s_movk_i32 s11, 0x7fff
	s_mov_b32 s12, 0xffff0000
	v_lshlrev_b32_e32 v4, 2, v2
	v_add_u32_e32 v28, 0x400, v20
	v_add_u32_e32 v29, 0x800, v20
	v_add_u32_e32 v30, 0xc00, v20
	v_add_u32_e32 v31, 0x1000, v20
	v_add_u32_e32 v32, 0x1400, v20
	v_add_u32_e32 v33, 0x1800, v20
	v_add_u32_e32 v34, 0x1c00, v20
	v_add_u32_e32 v35, 0x400, v22
	s_branch .LBB0_487
.LBB0_486:
	s_add_i32 s2, s2, s6
	s_add_i32 s7, s7, s8
	s_add_i32 s9, s9, s10
	s_cmp_lt_i32 s2, s99
	s_cbranch_scc0 .LBB0_499

	.amdhsa_kernel _Z9hymba_fwd4Args
		.amdhsa_group_segment_fixed_size 0
		.amdhsa_private_segment_fixed_size 0
		.amdhsa_kernarg_size 528
		.amdhsa_user_sgpr_count 2
		.amdhsa_user_sgpr_dispatch_ptr 0
		.amdhsa_user_sgpr_queue_ptr 0
		.amdhsa_user_sgpr_kernarg_segment_ptr 1
		.amdhsa_user_sgpr_dispatch_id 0
		.amdhsa_user_sgpr_kernarg_preload_length 0
		.amdhsa_user_sgpr_kernarg_preload_offset 0
		.amdhsa_user_sgpr_private_segment_size 0
		.amdhsa_uses_dynamic_stack 0
		.amdhsa_enable_private_segment 0
		.amdhsa_system_sgpr_workgroup_id_x 1
		.amdhsa_system_sgpr_workgroup_id_y 0
		.amdhsa_system_sgpr_workgroup_id_z 0
		.amdhsa_system_sgpr_workgroup_info 0
		.amdhsa_system_vgpr_workitem_id 0
		.amdhsa_next_free_vgpr 256
		.amdhsa_next_free_sgpr 100
		.amdhsa_accum_offset 256
		.amdhsa_reserve_vcc 1
		.amdhsa_float_round_mode_32 0
		.amdhsa_float_round_mode_16_64 0
		.amdhsa_float_denorm_mode_32 3
		.amdhsa_float_denorm_mode_16_64 3
		.amdhsa_dx10_clamp 1
		.amdhsa_ieee_mode 1
		.amdhsa_fp16_overflow 0
		.amdhsa_tg_split 0
		.amdhsa_exception_fp_ieee_invalid_op 0
		.amdhsa_exception_fp_denorm_src 0
		.amdhsa_exception_fp_ieee_div_zero 0
		.amdhsa_exception_fp_ieee_overflow 0
		.amdhsa_exception_fp_ieee_underflow 0
		.amdhsa_exception_fp_ieee_inexact 0
		.amdhsa_exception_int_div_zero 0
	.end_amdhsa_kernel

amdhsa.kernels:
  - .agpr_count:     0
    .args:
      - .offset:         0
        .size:           272
        .value_kind:     by_value
      - .offset:         272
        .size:           4
        .value_kind:     hidden_block_count_x
      - .offset:         276
        .size:           4
        .value_kind:     hidden_block_count_y
      - .offset:         280
        .size:           4
        .value_kind:     hidden_block_count_z
      - .offset:         284
        .size:           2
        .value_kind:     hidden_group_size_x
      - .offset:         286
        .size:           2
        .value_kind:     hidden_group_size_y
      - .offset:         288
        .size:           2
        .value_kind:     hidden_group_size_z
      - .offset:         290
        .size:           2
        .value_kind:     hidden_remainder_x
      - .offset:         292
        .size:           2
        .value_kind:     hidden_remainder_y
      - .offset:         294
        .size:           2
        .value_kind:     hidden_remainder_z
      - .offset:         312
        .size:           8
        .value_kind:     hidden_global_offset_x
      - .offset:         320
        .size:           8
        .value_kind:     hidden_global_offset_y
      - .offset:         328
        .size:           8
        .value_kind:     hidden_global_offset_z
      - .offset:         336
        .size:           2
        .value_kind:     hidden_grid_dims
      - .offset:         392
        .size:           4
        .value_kind:     hidden_dynamic_lds_size
    .group_segment_fixed_size: 0
    .kernarg_segment_align: 8
    .kernarg_segment_size: 528
    .language:       OpenCL C
    .language_version:
      - 2
      - 0
    .max_flat_workgroup_size: 512
    .name:           _Z9hymba_fwd4Args
    .private_segment_fixed_size: 0
    .sgpr_count:     106
    .sgpr_spill_count: 53
    .symbol:         _Z9hymba_fwd4Args.kd
    .uniform_work_group_size: 1
    .uses_dynamic_stack: false
    .vgpr_count:     256
    .vgpr_spill_count: 0
    .wavefront_size: 64
